# final RMSNorm loop: gains hoisted, next row prefetched, no waits on streaming stores
# baseline (speedup 1.0000x reference)
; __device__ __forceinline__ float bflo(unsigned u) { return __uint_as_float(u << 16); }
; __device__ __forceinline__ float bfhi(unsigned u) { return __uint_as_float(u & 0xffff0000u); }
; #define INP(k) ldptr(PT, (k))
; __global__ void __launch_bounds__(NTHR, 2) hybrid_fwd(Args args) {
;     ...
;     { const float* nfin = INP(13); const bf16* XBf = (const bf16*)(ws + WS_XB);
;       for (int m = gw; m < S; m += NGW) { const __attribute__((address_space(1))) v2u* xr = (const __attribute__((address_space(1))) v2u*)(XBf + (size_t)m * DM) + lane; f32x4 v[4]; float ss = 0.f;
; #pragma unroll
;         for (int j = 0; j < 4; ++j) { const v2u u = xr[64 * j]; v[j] = (f32x4){bflo(u.x), bfhi(u.x), bflo(u.y), bfhi(u.y)}; ss += (v[j][0] * v[j][0] + v[j][1] * v[j][1]) + (v[j][2] * v[j][2] + v[j][3] * v[j][3]); }
;         const float rs = __builtin_amdgcn_rsqf(wave_sum(ss) * (1.0f / 1024.0f) + EPS);
;         __attribute__((address_space(1))) f32x4* orow = (__attribute__((address_space(1))) f32x4*)(xo + (size_t)m * DM) + lane;
; #pragma unroll
;         for (int j = 0; j < 4; ++j) { const f32x4 g = *((const __attribute__((address_space(1))) f32x4*)nfin + lane + 64 * j); __builtin_nontemporal_store(v[j] * rs * g, orow + 64 * j); } } }
.LBB0_413:
	s_add_i32 s0, 0, 0x23f68
	v_mov_b32_e32 v0, s0
	s_add_i32 s0, 0, 0x23f6c
	v_mov_b32_e32 v1, s0
	ds_read_b32 v0, v0
	ds_read_b32 v1, v1
	s_cmpk_gt_i32 s84, 0x3fff
	s_waitcnt lgkmcnt(1)
	v_readfirstlane_b32 s0, v0
	s_waitcnt lgkmcnt(0)
	v_readfirstlane_b32 s1, v1
	s_cbranch_scc1 .LBB0_416
	v_readlane_b32 s4, v253, 26
	v_readlane_b32 s12, v253, 34
	v_readlane_b32 s13, v253, 35
	v_readlane_b32 s14, v253, 36
	v_readlane_b32 s15, v253, 37
	v_readlane_b32 s16, v253, 38
	v_readlane_b32 s17, v253, 39
	v_lshlrev_b32_e32 v4, 4, v219
	v_mov_b32_e32 v5, 0
	s_ashr_i32 s85, s84, 31
	v_readlane_b32 s18, v253, 40
	v_readlane_b32 s19, v253, 41
	s_mov_b64 s[12:13], s[16:17]
	v_lshl_add_u64 v[0:1], s[0:1], 0, v[4:5]
	s_lshl_b64 s[0:1], s[84:85], 11
	s_mov_b64 s[14:15], s[18:19]
	s_add_u32 s0, s14, s0
	v_lshlrev_b32_e32 v2, 3, v219
	v_mov_b32_e32 v3, v5
	s_addc_u32 s1, s15, s1
	v_lshl_add_u64 v[2:3], s[0:1], 0, v[2:3]
	s_mov_b64 s[0:1], 0x6205600
	v_lshl_add_u64 v[2:3], v[2:3], 0, s[0:1]
	s_lshl_b64 s[0:1], s[84:85], 12
	s_add_u32 s0, s12, s0
	s_addc_u32 s1, s13, s1
	v_lshl_add_u64 v[4:5], s[0:1], 0, v[4:5]
	s_mov_b64 s[0:1], 0x800
	v_lshl_add_u64 v[4:5], v[4:5], 0, s[0:1]
	v_mov_b32_e32 v6, 0x358637bd
	v_readlane_b32 s5, v253, 27
	v_readlane_b32 s6, v253, 28
	v_readlane_b32 s7, v253, 29
	v_readlane_b32 s8, v253, 30
	v_readlane_b32 s9, v253, 31
	v_readlane_b32 s10, v253, 32
	v_readlane_b32 s11, v253, 33
	global_load_dwordx4 v[44:47], v[0:1], off
	global_load_dwordx4 v[48:51], v[0:1], off offset:1024
	global_load_dwordx4 v[52:55], v[0:1], off offset:2048
	global_load_dwordx4 v[56:59], v[0:1], off offset:3072
	global_load_dwordx2 v[60:61], v[2:3], off offset:-1536
	global_load_dwordx2 v[62:63], v[2:3], off offset:-1024
	global_load_dwordx2 v[64:65], v[2:3], off offset:-512
	global_load_dwordx2 v[66:67], v[2:3], off
	s_waitcnt vmcnt(0)
.LBB0_415:
	v_mov_b32_e32 v12, v60
	v_mov_b32_e32 v13, v61
	v_mov_b32_e32 v14, v62
	v_mov_b32_e32 v15, v63
	v_mov_b32_e32 v16, v64
	v_mov_b32_e32 v17, v65
	v_mov_b32_e32 v18, v66
	v_mov_b32_e32 v19, v67
	s_add_i32 s84, s84, s94
	v_lshl_add_u64 v[2:3], v[2:3], 0, s[30:31]
	s_cmpk_gt_i32 s84, 0x3fff
	s_cbranch_scc1 .Lfin_nopf
	global_load_dwordx2 v[60:61], v[2:3], off offset:-1536
	global_load_dwordx2 v[62:63], v[2:3], off offset:-1024
	global_load_dwordx2 v[64:65], v[2:3], off offset:-512
	global_load_dwordx2 v[66:67], v[2:3], off
.Lfin_nopf:
	v_lshlrev_b32_e32 v20, 16, v12
	v_and_b32_e32 v21, 0xffff0000, v12
	v_lshlrev_b32_e32 v12, 16, v13
	v_and_b32_e32 v13, 0xffff0000, v13
	v_lshlrev_b32_e32 v23, 16, v15
	v_lshlrev_b32_e32 v22, 16, v14
	v_and_b32_e32 v15, 0xffff0000, v15
	v_and_b32_e32 v14, 0xffff0000, v14
	v_and_b32_e32 v25, 0xffff0000, v16
	v_lshlrev_b32_e32 v27, 16, v18
	v_and_b32_e32 v29, 0xffff0000, v18
	v_mul_f32_e32 v26, v13, v13
	v_mul_f32_e32 v28, v21, v21
	v_lshlrev_b32_e32 v24, 16, v16
	v_lshlrev_b32_e32 v16, 16, v17
	v_and_b32_e32 v17, 0xffff0000, v17
	v_pk_mul_f32 v[30:31], v[14:15], v[14:15]
	v_mov_b32_e32 v33, v27
	v_mul_f32_e32 v32, v25, v25
	v_pk_fma_f32 v[36:37], v[12:13], v[12:13], v[26:27] op_sel_hi:[1,1,0]
	v_pk_fma_f32 v[38:39], v[20:21], v[20:21], v[28:29] op_sel_hi:[1,1,0]
	v_lshlrev_b32_e32 v18, 16, v19
	v_and_b32_e32 v19, 0xffff0000, v19
	v_mul_f32_e32 v34, v17, v17
	v_pk_fma_f32 v[30:31], v[22:23], v[22:23], v[30:31]
	v_pk_fma_f32 v[40:41], v[24:25], v[24:25], v[32:33] op_sel_hi:[1,1,0]
	v_mov_b32_e32 v26, v38
	v_mov_b32_e32 v32, v36
	v_mul_f32_e32 v7, v29, v29
	v_mul_f32_e32 v42, v18, v18
	v_mul_f32_e32 v43, v19, v19
	v_pk_fma_f32 v[34:35], v[16:17], v[16:17], v[34:35] op_sel_hi:[1,1,0]
	v_pk_add_f32 v[36:37], v[38:39], v[36:37]
	v_pk_add_f32 v[30:31], v[30:31], v[30:31] op_sel:[0,1] op_sel_hi:[1,0]
	v_pk_mul_f32 v[32:33], v[26:27], v[32:33]
	v_mov_b32_e32 v41, v42
	v_mov_b32_e32 v35, v43
	v_mov_b32_e32 v31, v7
	v_mov_b32_e32 v37, v33
	v_pk_add_f32 v[34:35], v[40:41], v[34:35]
	v_pk_add_f32 v[30:31], v[36:37], v[30:31]
	v_mov_b32_e32 v28, v27
	v_pk_add_f32 v[30:31], v[30:31], v[34:35]
	s_nop 0
	v_add_f32_e32 v7, v30, v31
	s_nop 1
	v_add_f32_dpp v7, v7, v7 quad_perm:[1,0,3,2] row_mask:0xf bank_mask:0xf bound_ctrl:1
	s_nop 1
	v_add_f32_dpp v7, v7, v7 quad_perm:[2,3,0,1] row_mask:0xf bank_mask:0xf bound_ctrl:1
	s_nop 1
	v_add_f32_dpp v7, v7, v7 row_half_mirror row_mask:0xf bank_mask:0xf bound_ctrl:1
	s_nop 1
	v_add_f32_dpp v7, v7, v7 row_mirror row_mask:0xf bank_mask:0xf bound_ctrl:1
	s_nop 0
	v_readlane_b32 s2, v7, 16
	v_readlane_b32 s3, v7, 48
	v_readlane_b32 s0, v7, 0
	v_readlane_b32 s1, v7, 32
	v_mov_b32_e32 v30, s2
	v_mov_b32_e32 v31, s3
	v_pk_add_f32 v[30:31], s[0:1], v[30:31]
	s_nop 0
	v_add_f32_e32 v7, v30, v31
	v_fmamk_f32 v7, v7, 0x3a800000, v6
	v_rsq_f32_e32 v26, v7
	s_nop 0
	v_pk_mul_f32 v[20:21], v[26:27], v[20:21] op_sel_hi:[0,1]
	v_pk_mul_f32 v[12:13], v[26:27], v[12:13] op_sel_hi:[0,1]
	v_pk_mul_f32 v[10:11], v[12:13], v[46:47]
	v_pk_mul_f32 v[8:9], v[20:21], v[44:45]
	global_store_dwordx4 v[4:5], v[8:11], off offset:-2048 nt
	v_mov_b32_e32 v12, v23
	v_mov_b32_e32 v13, v15
	v_mov_b32_e32 v23, v14
	v_pk_mul_f32 v[12:13], v[26:27], v[12:13] op_sel_hi:[0,1]
	v_pk_mul_f32 v[14:15], v[26:27], v[22:23] op_sel_hi:[0,1]
	v_pk_mul_f32 v[68:69], v[14:15], v[48:49]
	v_pk_mul_f32 v[70:71], v[12:13], v[50:51]
	global_store_dwordx4 v[4:5], v[68:71], off offset:-1024 nt
	v_pk_mul_f32 v[12:13], v[26:27], v[16:17] op_sel_hi:[0,1]
	v_pk_mul_f32 v[14:15], v[26:27], v[24:25] op_sel_hi:[0,1]
	v_pk_mul_f32 v[72:73], v[14:15], v[52:53]
	v_pk_mul_f32 v[74:75], v[12:13], v[54:55]
	global_store_dwordx4 v[4:5], v[72:75], off nt
	v_pk_mul_f32 v[12:13], v[26:27], v[18:19] op_sel_hi:[0,1]
	v_pk_mul_f32 v[14:15], v[26:27], v[28:29] op_sel_hi:[0,1]
	v_pk_mul_f32 v[76:77], v[14:15], v[56:57]
	v_pk_mul_f32 v[78:79], v[12:13], v[58:59]
	global_store_dwordx4 v[4:5], v[76:79], off offset:1024 nt
	v_lshl_add_u64 v[4:5], v[4:5], 0, s[34:35]
	s_waitcnt vmcnt(4)
	s_cmpk_gt_i32 s84, 0x3fff
	s_cbranch_scc0 .LBB0_415
